# k34 with the static GEMM priority given to waves 0-3 (the un-staggered group) instead of waves 4-7
# speedup vs baseline: 1.0151x; 1.0006x over previous
; #define PG8_STAGE(bufoff, gbase, voff) do { _Pragma("unroll") for (int _i = 0; _i < 2; ++_i) \
;         __builtin_amdgcn_global_load_lds((const unsigned*)((const char*)(gbase) + (voff)[_i]), (LAS unsigned*)(lds + (bufoff) + ldsw + _i * 8192), 16, 0, 0); } while (0)
; #define PG8_BAR __builtin_amdgcn_s_barrier()
;     __host__ __device__ bool next(int i, Unit& u) const {
;         const long L = (long)i * G + c; if (L >= nwg) return false;
;         int wgid = (int)L; { const int q = nwg / NXCD, r = nwg % NXCD, xcd = wgid % NXCD, off = wgid / NXCD; wgid = (xcd < r ? xcd * (q + 1) : r * (q + 1) + (xcd - r) * q) + off; }
;         const int nig = WGM * nN, gid = wgid / nig, fm = gid * WGM, gsz = (nM - fm) < WGM ? (nM - fm) : WGM;
;         u.pm = fm + ((wgid % nig) % gsz); u.pn = (wgid % nig) / gsz; if (cperm) u.pn = (u.pn % 5) * 8 + u.pn / 5; return true;
; template <class Epi, bool ALIGN_EPI, class Hook = NoHook>
; __device__ __forceinline__ void gemm_phase(LAS unsigned char* lds, const Gemm g, const StaticOrder& S, const Epi& E, const Hook& HK = Hook()) {
;     ...
;     for (int i = 0; i < 2; ++i) { int R, C; stage_rc(tid * 16 + i * 8192, R, C); const int Rb = Epi::PERM ? ((R & ~31) + perm32(R & 31)) : R;
;         voffA[i] = (unsigned)(R * g.lda + C) * 2u; voffB[i] = (unsigned)(Rb * g.ldb + C) * 2u; }
;     const size_t kstep = (size_t)(BK * 2);
;     const size_t hstepA = (size_t)HALF * g.lda * 2, hstepB = (size_t)HALF * g.ldb * 2;
;     const size_t tstepA = 2 * hstepA, tstepB = 2 * hstepB;
;     const unsigned ldsw = (unsigned)wid * 1024u;
;     const int aoff = lds_byte(wr * 64 + fr, fq * 8), boff = lds_byte(wc * 32 + fr, fq * 8);
;     ...
;     Unit cur, nxt; int ui = 0;
;     if (!S.next(0, cur)) return;
;     f32x4 acc[2][2][4][2];
; #pragma unroll
;     for (int a = 0; a < 2; ++a)
; #pragma unroll
;         for (int b = 0; b < 2; ++b)
; #pragma unroll
;             for (int m = 0; m < 4; ++m)
; #pragma unroll
;                 for (int n = 0; n < 2; ++n) acc[a][b][m][n] = (f32x4){0.f, 0.f, 0.f, 0.f};
;     bf16x8 At[4][2], B0[2][2], B1[2][2];
;     const char* cA = (const char*)g.A + (size_t)cur.pm * tstepA; const char* cB = (const char*)g.Bt + (size_t)cur.pn * tstepB;
;     PG8_STAGE(PG8_SB(0, 0), cB, voffB); PG8_STAGE(PG8_SB(0, 1), cB + hstepB, voffB); PG8_STAGE(PG8_SA(0, 0), cA, voffA); PG8_STAGE(PG8_SA(0, 1), cA + hstepA, voffA);
;     if (wr == 1) PG8_BAR;
.LBB0_39:
	s_or_b64 exec, exec, s[0:1]
	s_add_u32 s48, s62, 0x7c00000
	s_addc_u32 s49, s63, 0
	s_add_u32 s46, s62, 0xbc00000
	s_addc_u32 s47, s63, 0
	s_cmpk_lt_i32 s2, 0xb00
	s_cselect_b64 s[0:1], -1, 0
	v_writelane_b32 v254, s0, 16
	v_mov_b32_e32 v9, v136
	s_barrier
	v_writelane_b32 v254, s1, 17
	s_cmpk_gt_i32 s2, 0xaff
	v_readfirstlane_b32 s1, v9
	v_writelane_b32 v254, s56, 18
	s_nop 1
	v_writelane_b32 v254, s57, 19
	s_cbranch_scc1 .LBB0_55
	v_lshlrev_b32_e32 v0, 4, v9
	v_add_u32_e32 v1, 0x2000, v0
	v_ashrrev_i32_e32 v2, 31, v1
	v_lshrrev_b32_e32 v2, 22, v2
	v_add_u32_e32 v2, v1, v2
	v_ashrrev_i32_e32 v8, 10, v2
	v_mul_i32_i24_e32 v2, 0x400, v8
	v_sub_u32_e32 v1, v1, v2
	v_lshrrev_b32_e32 v2, 4, v1
	v_bitop3_b32 v1, v2, v1, 32 bitop3:0x6c
	v_ashrrev_i32_e32 v2, 31, v1
	v_lshrrev_b32_e32 v2, 26, v2
	v_add_u32_e32 v2, v1, v2
	v_lshlrev_b32_e32 v3, 3, v8
	v_ashrrev_i32_e32 v10, 6, v2
	v_and_b32_e32 v3, -16, v3
	v_add_u32_e32 v3, v10, v3
	v_and_b32_e32 v4, 3, v10
	s_mov_b32 s0, 0xfffe0
	v_lshrrev_b32_e32 v5, 2, v3
	v_lshlrev_b32_e32 v6, 1, v3
	v_and_b32_e32 v2, 0xc0, v2
	v_and_or_b32 v4, v3, s0, v4
	v_and_b32_e32 v5, 4, v5
	v_and_b32_e32 v6, 24, v6
	v_sub_u32_e32 v1, v1, v2
	v_mov_b32_e32 v2, 1
	v_or3_b32 v4, v4, v5, v6
	v_lshlrev_b32_e32 v5, 5, v8
	v_ashrrev_i16_sdwa v1, v2, sext(v1) dst_sel:DWORD dst_unused:UNUSED_PAD src0_sel:DWORD src1_sel:BYTE_0
	v_and_b32_e32 v5, 32, v5
	v_bfe_i32 v11, v1, 0, 16
	v_add_lshl_u32 v1, v5, v11, 1
	v_lshl_add_u32 v128, v4, 12, v1
	v_lshl_add_u32 v130, v3, 12, v1
	v_bfe_i32 v1, v9, 27, 1
	v_lshrrev_b32_e32 v1, 22, v1
	v_add_u32_e32 v1, v0, v1
	v_and_b32_e32 v1, 0xfffffc00, v1
	v_sub_u32_e32 v0, v0, v1
	v_lshrrev_b32_e32 v1, 4, v0
	v_ashrrev_i32_e32 v3, 31, v9
	v_bitop3_b32 v0, v1, v0, 32 bitop3:0x6c
	v_lshrrev_b32_e32 v3, 26, v3
	v_ashrrev_i32_e32 v1, 31, v0
	v_add_u32_e32 v3, v9, v3
	v_lshrrev_b32_e32 v1, 26, v1
	v_ashrrev_i32_e32 v13, 6, v3
	v_add_u32_e32 v1, v0, v1
	v_lshlrev_b32_e32 v3, 3, v13
	v_ashrrev_i32_e32 v12, 6, v1
	v_and_b32_e32 v3, -16, v3
	v_add_u32_e32 v3, v12, v3
	v_and_b32_e32 v4, 3, v12
	s_ashr_i32 s50, s2, 31
	v_and_or_b32 v4, v3, s0, v4
	s_lshr_b32 s0, s50, 29
	s_add_i32 s0, s2, s0
	s_ashr_i32 s6, s1, 6
	s_ashr_i32 s4, s0, 3
	s_and_b32 s0, s0, -8
	s_ashr_i32 s7, s1, 8
	s_lshl_b32 s17, s6, 10
	s_sub_i32 s0, s2, s0
	s_cmp_lt_i32 s0, 0
	s_movk_i32 s51, 0x161
	s_cselect_b32 s5, s51, 0x160
	s_mul_i32 s0, s0, s5
	s_add_i32 s0, s0, s4
	s_mul_hi_i32 s4, s0, 0x2e8ba2e9
	s_lshr_b32 s5, s4, 31
	s_ashr_i32 s4, s4, 6
	s_add_i32 s4, s4, s5
	s_lshl_b32 s5, s4, 3
	s_mulk_i32 s4, 0x160
	s_sub_i32 s4, s0, s4
	s_sext_i32_i16 s0, s4
	s_bfe_u32 s0, s0, 0x3001c
	s_add_i32 s12, s4, s0
	s_sext_i32_i16 s0, s12
	s_and_b32 s12, s12, 0xfff8
	s_sub_i32 s4, s4, s12
	s_sext_i32_i16 s4, s4
	v_lshrrev_b32_e32 v5, 2, v3
	v_lshlrev_b32_e32 v6, 1, v3
	v_and_b32_e32 v1, 0xc0, v1
	s_lshr_b32 s0, s0, 3
	s_add_i32 s82, s5, s4
	v_and_b32_e32 v5, 4, v5
	v_and_b32_e32 v6, 24, v6
	v_sub_u32_e32 v0, v0, v1
	s_ashr_i32 s83, s82, 31
	s_bfe_i64 s[12:13], s[0:1], 0x100000
	v_or3_b32 v4, v4, v5, v6
	v_lshlrev_b32_e32 v5, 5, v13
	v_ashrrev_i16_sdwa v0, v2, sext(v0) dst_sel:DWORD dst_unused:UNUSED_PAD src0_sel:DWORD src1_sel:BYTE_0
	s_lshl_b64 s[4:5], s[82:83], 20
	s_lshl_b64 s[12:13], s[12:13], 20
	v_and_b32_e32 v5, 32, v5
	v_bfe_i32 v14, v0, 0, 16
	s_add_u32 s86, s66, s12
	v_add_lshl_u32 v0, v5, v14, 1
	s_addc_u32 s87, s67, s13
	s_add_i32 s71, s17, 0
	v_lshl_add_u32 v132, v4, 12, v0
	s_add_i32 m0, s71, 0x10000
	v_lshl_add_u32 v134, v3, 12, v0
	global_load_lds_dwordx4 v132, s[86:87]
	s_add_i32 m0, s71, 0x12000
	s_add_u32 s12, s86, 0x80000
	global_load_lds_dwordx4 v128, s[86:87]
	s_addc_u32 s13, s87, 0
	s_add_i32 m0, s71, 0x14000
	v_mov_b32_e32 v133, 0
	global_load_lds_dwordx4 v132, s[12:13]
	s_add_i32 m0, s71, 0x16000
	s_add_u32 s84, s48, s4
	s_addc_u32 s85, s49, s5
	s_add_i32 s72, s71, 0x2000
	global_load_lds_dwordx4 v128, s[12:13]
	s_mov_b32 m0, s71
	s_add_u32 s4, s84, 0x80000
	global_load_lds_dwordx4 v134, s[84:85]
	s_mov_b32 m0, s72
	s_addc_u32 s5, s85, 0
	s_add_i32 s73, s71, 0x4000
	global_load_lds_dwordx4 v130, s[84:85]
	s_mov_b32 m0, s73
	s_add_i32 s83, s71, 0x6000
	global_load_lds_dwordx4 v134, s[4:5]
	s_mov_b32 m0, s83
	v_mov_b32_e32 v129, v133
	global_load_lds_dwordx4 v130, s[4:5]
	v_mov_b32_e32 v135, v133
	v_mov_b32_e32 v131, v133
	s_cmp_eq_u32 s7, 1
	s_mov_b32 s90, 0
	v_lshl_add_u64 v[6:7], s[86:87], 0, v[132:133]
	v_lshl_add_u64 v[4:5], s[86:87], 0, v[128:129]
	v_lshl_add_u64 v[0:1], s[84:85], 0, v[134:135]
	s_cselect_b64 s[4:5], -1, 0
	s_cmp_lg_u32 s7, 1
	v_lshl_add_u64 v[2:3], s[84:85], 0, v[130:131]
	s_cbranch_scc1 .Lprio_inv_0
	s_barrier
	s_branch .LBB0_42
.Lprio_inv_0:
	s_setprio 1

; #define PG8_STAGE(bufoff, gbase, voff) do { _Pragma("unroll") for (int _i = 0; _i < 2; ++_i) \
;         __builtin_amdgcn_global_load_lds((const unsigned*)((const char*)(gbase) + (voff)[_i]), (LAS unsigned*)(lds + (bufoff) + ldsw + _i * 8192), 16, 0, 0); } while (0)
; #define PG8_BAR __builtin_amdgcn_s_barrier()
;     __host__ __device__ bool next(int i, Unit& u) const {
;         const long L = (long)i * G + c; if (L >= nwg) return false;
;         int wgid = (int)L; { const int q = nwg / NXCD, r = nwg % NXCD, xcd = wgid % NXCD, off = wgid / NXCD; wgid = (xcd < r ? xcd * (q + 1) : r * (q + 1) + (xcd - r) * q) + off; }
;         const int nig = WGM * nN, gid = wgid / nig, fm = gid * WGM, gsz = (nM - fm) < WGM ? (nM - fm) : WGM;
;         u.pm = fm + ((wgid % nig) % gsz); u.pn = (wgid % nig) / gsz; if (cperm) u.pn = (u.pn % 5) * 8 + u.pn / 5; return true;
; template <class Epi, bool ALIGN_EPI, class Hook = NoHook>
; __device__ __forceinline__ void gemm_phase(LAS unsigned char* lds, const Gemm g, const StaticOrder& S, const Epi& E, const Hook& HK = Hook()) {
;     ...
;     for (int i = 0; i < 2; ++i) { int R, C; stage_rc(tid * 16 + i * 8192, R, C); const int Rb = Epi::PERM ? ((R & ~31) + perm32(R & 31)) : R;
;         voffA[i] = (unsigned)(R * g.lda + C) * 2u; voffB[i] = (unsigned)(Rb * g.ldb + C) * 2u; }
;     const size_t kstep = (size_t)(BK * 2);
;     const size_t hstepA = (size_t)HALF * g.lda * 2, hstepB = (size_t)HALF * g.ldb * 2;
;     const size_t tstepA = 2 * hstepA, tstepB = 2 * hstepB;
;     const unsigned ldsw = (unsigned)wid * 1024u;
;     const int aoff = lds_byte(wr * 64 + fr, fq * 8), boff = lds_byte(wc * 32 + fr, fq * 8);
;     ...
;     Unit cur, nxt; int ui = 0;
;     if (!S.next(0, cur)) return;
;     f32x4 acc[2][2][4][2];
; #pragma unroll
;     for (int a = 0; a < 2; ++a)
; #pragma unroll
;         for (int b = 0; b < 2; ++b)
; #pragma unroll
;             for (int m = 0; m < 4; ++m)
; #pragma unroll
;                 for (int n = 0; n < 2; ++n) acc[a][b][m][n] = (f32x4){0.f, 0.f, 0.f, 0.f};
;     bf16x8 At[4][2], B0[2][2], B1[2][2];
;     const char* cA = (const char*)g.A + (size_t)cur.pm * tstepA; const char* cB = (const char*)g.Bt + (size_t)cur.pn * tstepB;
;     PG8_STAGE(PG8_SB(0, 0), cB, voffB); PG8_STAGE(PG8_SB(0, 1), cB + hstepB, voffB); PG8_STAGE(PG8_SA(0, 0), cA, voffA); PG8_STAGE(PG8_SA(0, 1), cA + hstepA, voffA);
;     if (wr == 1) PG8_BAR;
.LBB0_112:
	v_ashrrev_i32_e32 v1, 31, v8
	v_lshrrev_b32_e32 v1, 26, v1
	v_add_u32_e32 v1, v8, v1
	v_ashrrev_i32_e32 v9, 6, v1
	v_bfe_i32 v1, v8, 27, 1
	v_lshlrev_b32_e32 v0, 4, v8
	v_lshrrev_b32_e32 v1, 22, v1
	v_add_u32_e32 v1, v0, v1
	v_and_b32_e32 v1, 0xfffffc00, v1
	v_sub_u32_e32 v1, v0, v1
	v_lshrrev_b32_e32 v2, 4, v1
	v_bitop3_b32 v1, v2, v1, 32 bitop3:0x6c
	v_ashrrev_i32_e32 v3, 31, v1
	v_lshrrev_b32_e32 v3, 26, v3
	v_lshlrev_b32_e32 v2, 3, v9
	v_add_u32_e32 v3, v1, v3
	v_and_b32_e32 v2, -16, v2
	v_ashrrev_i32_e32 v10, 6, v3
	v_and_b32_e32 v3, 0xc0, v3
	v_add_u32_e32 v2, v10, v2
	v_lshlrev_b32_e32 v4, 5, v9
	v_sub_u32_e32 v1, v1, v3
	v_mov_b32_e32 v3, 1
	s_ashr_i32 s7, s6, 3
	v_and_b32_e32 v11, 32, v4
	v_ashrrev_i16_sdwa v1, v3, sext(v1) dst_sel:DWORD dst_unused:UNUSED_PAD src0_sel:DWORD src1_sel:BYTE_0
	v_lshlrev_b32_e32 v4, 1, v2
	v_lshrrev_b32_e32 v5, 2, v2
	v_and_b32_e32 v6, 3, v10
	s_mov_b32 s6, 0x7fffe0
	v_bfe_i32 v12, v1, 0, 16
	v_and_b32_e32 v4, 24, v4
	v_and_b32_e32 v5, 4, v5
	v_and_or_b32 v6, v2, s6, v6
	s_movk_i32 s1, 0x1600
	v_add_u32_e32 v1, v11, v12
	v_or3_b32 v4, v6, v5, v4
	v_mul_lo_u32 v2, v2, s1
	v_add_lshl_u32 v144, v1, v2, 1
	v_mul_u32_u24_e32 v2, 0x1600, v4
	v_add_u32_e32 v0, 0x2000, v0
	v_add_lshl_u32 v146, v2, v1, 1
	v_ashrrev_i32_e32 v1, 31, v0
	v_lshrrev_b32_e32 v1, 22, v1
	s_add_i32 s5, s5, s7
	v_add_u32_e32 v1, v0, v1
	s_ashr_i32 s7, s5, 31
	v_ashrrev_i32_e32 v13, 10, v1
	s_lshr_b32 s7, s7, 27
	v_mul_i32_i24_e32 v1, 0x400, v13
	s_add_i32 s7, s5, s7
	v_sub_u32_e32 v0, v0, v1
	s_ashr_i32 s12, s7, 5
	s_andn2_b32 s7, s7, 31
	v_lshrrev_b32_e32 v1, 4, v0
	s_sub_i32 s7, s5, s7
	v_bitop3_b32 v0, v1, v0, 32 bitop3:0x6c
	s_bfe_i32 s5, s7, 0x80000
	v_ashrrev_i32_e32 v2, 31, v0
	s_bfe_u32 s5, s5, 0x2000d
	v_lshrrev_b32_e32 v2, 26, v2
	s_add_i32 s13, s7, s5
	v_lshlrev_b32_e32 v1, 3, v13
	v_add_u32_e32 v2, v0, v2
	s_bfe_i32 s5, s13, 0x80000
	s_and_b32 s13, s13, 0xfc
	v_and_b32_e32 v1, -16, v1
	v_ashrrev_i32_e32 v14, 6, v2
	v_lshlrev_b32_e32 v4, 5, v13
	s_sub_i32 s7, s7, s13
	v_add_u32_e32 v1, v14, v1
	v_and_b32_e32 v15, 32, v4
	v_and_b32_e32 v4, 3, v14
	s_lshl_b32 s12, s12, 2
	s_sext_i32_i16 s14, s5
	s_sext_i32_i8 s7, s7
	v_and_b32_e32 v2, 0xc0, v2
	v_and_or_b32 v4, v1, s6, v4
	s_ashr_i32 s6, s4, 6
	s_add_i32 s92, s12, s7
	s_ashr_i32 s12, s14, 2
	s_ashr_i32 s0, s4, 8
	v_sub_u32_e32 v0, v0, v2
	s_lshl_b32 s27, s6, 10
	s_lshr_b32 s5, s14, 2
	s_mul_hi_i32 s13, s12, 0x2c0000
	s_mul_i32 s12, s12, 0x2c0000
	v_ashrrev_i16_sdwa v0, v3, sext(v0) dst_sel:DWORD dst_unused:UNUSED_PAD src0_sel:DWORD src1_sel:BYTE_0
	v_lshlrev_b32_e32 v2, 1, v1
	v_lshrrev_b32_e32 v3, 2, v1
	s_add_u32 s28, s56, s12
	v_bfe_i32 v16, v0, 0, 16
	v_and_b32_e32 v2, 24, v2
	v_and_b32_e32 v3, 4, v3
	s_addc_u32 s29, s57, s13
	s_add_i32 s50, s27, 0
	v_add_u32_e32 v0, v15, v16
	v_or3_b32 v2, v4, v3, v2
	v_mul_lo_u32 v1, v1, s1
	s_add_i32 m0, s50, 0x10000
	v_add_lshl_u32 v148, v0, v1, 1
	v_mul_u32_u24_e32 v1, 0x1600, v2
	global_load_lds_dwordx4 v146, s[28:29]
	s_add_i32 m0, s50, 0x12000
	v_add_lshl_u32 v150, v1, v0, 1
	s_add_u32 s12, s28, 0x160000
	global_load_lds_dwordx4 v150, s[28:29]
	s_addc_u32 s13, s29, 0
	s_add_i32 m0, s50, 0x14000
	s_mul_i32 s15, s92, 0x2c0000
	global_load_lds_dwordx4 v146, s[12:13]
	s_add_i32 m0, s50, 0x16000
	s_mul_hi_i32 s7, s92, 0x2c0000
	s_add_u32 s24, s46, s15
	s_addc_u32 s25, s47, s7
	s_add_i32 s51, s50, 0x2000
	global_load_lds_dwordx4 v150, s[12:13]
	s_mov_b32 m0, s50
	s_add_u32 s12, s24, 0x160000
	global_load_lds_dwordx4 v144, s[24:25]
	s_mov_b32 m0, s51
	s_addc_u32 s13, s25, 0
	s_add_i32 s71, s50, 0x4000
	global_load_lds_dwordx4 v148, s[24:25]
	s_mov_b32 m0, s71
	s_add_i32 s72, s50, 0x6000
	global_load_lds_dwordx4 v144, s[12:13]
	s_mov_b32 m0, s72
	v_mov_b32_e32 v147, 0
	global_load_lds_dwordx4 v148, s[12:13]
	v_mov_b32_e32 v151, v147
	v_mov_b32_e32 v145, v147
	v_mov_b32_e32 v149, v147
	s_cmp_eq_u32 s0, 1
	s_mov_b32 s73, 0
	v_lshl_add_u64 v[6:7], s[28:29], 0, v[146:147]
	v_lshl_add_u64 v[2:3], s[28:29], 0, v[150:151]
	s_mov_b32 s7, 0x16000
	v_lshl_add_u64 v[0:1], s[24:25], 0, v[144:145]
	s_cselect_b64 s[12:13], -1, 0
	s_cmp_lg_u32 s0, 1
	v_lshl_add_u64 v[4:5], s[24:25], 0, v[148:149]
	s_cbranch_scc1 .Lprio_inv_1
	s_barrier
	s_branch .LBB0_114

; #define PG8_STAGE(bufoff, gbase, voff) do { _Pragma("unroll") for (int _i = 0; _i < 2; ++_i) \
;         __builtin_amdgcn_global_load_lds((const unsigned*)((const char*)(gbase) + (voff)[_i]), (LAS unsigned*)(lds + (bufoff) + ldsw + _i * 8192), 16, 0, 0); } while (0)
; #define PG8_BAR __builtin_amdgcn_s_barrier()
;     __host__ __device__ bool next(int i, Unit& u) const {
;         const long L = (long)i * G + c; if (L >= nwg) return false;
;         int wgid = (int)L; { const int q = nwg / NXCD, r = nwg % NXCD, xcd = wgid % NXCD, off = wgid / NXCD; wgid = (xcd < r ? xcd * (q + 1) : r * (q + 1) + (xcd - r) * q) + off; }
;         const int nig = WGM * nN, gid = wgid / nig, fm = gid * WGM, gsz = (nM - fm) < WGM ? (nM - fm) : WGM;
;         u.pm = fm + ((wgid % nig) % gsz); u.pn = (wgid % nig) / gsz; if (cperm) u.pn = (u.pn % 5) * 8 + u.pn / 5; return true;
; template <class Epi, bool ALIGN_EPI, class Hook = NoHook>
; __device__ __forceinline__ void gemm_phase(LAS unsigned char* lds, const Gemm g, const StaticOrder& S, const Epi& E, const Hook& HK = Hook()) {
;     ...
;     for (int i = 0; i < 2; ++i) { int R, C; stage_rc(tid * 16 + i * 8192, R, C); const int Rb = Epi::PERM ? ((R & ~31) + perm32(R & 31)) : R;
;         voffA[i] = (unsigned)(R * g.lda + C) * 2u; voffB[i] = (unsigned)(Rb * g.ldb + C) * 2u; }
;     const size_t kstep = (size_t)(BK * 2);
;     const size_t hstepA = (size_t)HALF * g.lda * 2, hstepB = (size_t)HALF * g.ldb * 2;
;     const size_t tstepA = 2 * hstepA, tstepB = 2 * hstepB;
;     const unsigned ldsw = (unsigned)wid * 1024u;
;     const int aoff = lds_byte(wr * 64 + fr, fq * 8), boff = lds_byte(wc * 32 + fr, fq * 8);
;     ...
;     Unit cur, nxt; int ui = 0;
;     if (!S.next(0, cur)) return;
;     f32x4 acc[2][2][4][2];
; #pragma unroll
;     for (int a = 0; a < 2; ++a)
; #pragma unroll
;         for (int b = 0; b < 2; ++b)
; #pragma unroll
;             for (int m = 0; m < 4; ++m)
; #pragma unroll
;                 for (int n = 0; n < 2; ++n) acc[a][b][m][n] = (f32x4){0.f, 0.f, 0.f, 0.f};
;     bf16x8 At[4][2], B0[2][2], B1[2][2];
;     const char* cA = (const char*)g.A + (size_t)cur.pm * tstepA; const char* cB = (const char*)g.Bt + (size_t)cur.pn * tstepB;
;     PG8_STAGE(PG8_SB(0, 0), cB, voffB); PG8_STAGE(PG8_SB(0, 1), cB + hstepB, voffB); PG8_STAGE(PG8_SA(0, 0), cA, voffA); PG8_STAGE(PG8_SA(0, 1), cA + hstepA, voffA);
;     if (wr == 1) PG8_BAR;
.LBB0_261:
	s_add_u32 s76, s62, 0x17c00000
	s_addc_u32 s77, s63, 0
	s_andn2_b64 vcc, exec, s[0:1]
	s_cbranch_vccnz .LBB0_349
	v_ashrrev_i32_e32 v1, 31, v8
	v_lshrrev_b32_e32 v1, 26, v1
	v_add_u32_e32 v1, v8, v1
	v_ashrrev_i32_e32 v9, 6, v1
	v_bfe_i32 v1, v8, 27, 1
	v_lshlrev_b32_e32 v0, 4, v8
	v_lshrrev_b32_e32 v1, 22, v1
	v_add_u32_e32 v1, v0, v1
	v_and_b32_e32 v1, 0xfffffc00, v1
	v_sub_u32_e32 v1, v0, v1
	v_lshrrev_b32_e32 v2, 4, v1
	v_bitop3_b32 v1, v2, v1, 32 bitop3:0x6c
	v_ashrrev_i32_e32 v3, 31, v1
	v_lshrrev_b32_e32 v3, 26, v3
	v_add_u32_e32 v3, v1, v3
	v_lshlrev_b32_e32 v2, 3, v9
	v_ashrrev_i32_e32 v10, 6, v3
	v_and_b32_e32 v3, 0xc0, v3
	v_and_b32_e32 v2, -16, v2
	v_sub_u32_e32 v1, v1, v3
	v_mov_b32_e32 v3, 1
	v_add_u32_e32 v2, v10, v2
	v_ashrrev_i16_sdwa v1, v3, sext(v1) dst_sel:DWORD dst_unused:UNUSED_PAD src0_sel:DWORD src1_sel:BYTE_0
	v_lshlrev_b32_e32 v4, 5, v9
	v_bfe_i32 v11, v1, 0, 16
	v_lshlrev_b32_e32 v1, 1, v2
	v_lshrrev_b32_e32 v5, 2, v2
	v_and_b32_e32 v6, 3, v10
	s_mov_b32 s1, 0xfffe0
	v_and_b32_e32 v4, 32, v4
	v_and_b32_e32 v1, 24, v1
	v_and_b32_e32 v5, 4, v5
	v_and_or_b32 v6, v2, s1, v6
	v_or3_b32 v1, v6, v5, v1
	v_add_lshl_u32 v4, v4, v11, 1
	v_add_u32_e32 v0, 0x2000, v0
	v_lshl_add_u32 v134, v1, 12, v4
	v_ashrrev_i32_e32 v1, 31, v0
	v_lshrrev_b32_e32 v1, 22, v1
	v_add_u32_e32 v1, v0, v1
	v_ashrrev_i32_e32 v12, 10, v1
	v_mul_i32_i24_e32 v1, 0x400, v12
	v_sub_u32_e32 v0, v0, v1
	v_lshrrev_b32_e32 v1, 4, v0
	v_bitop3_b32 v0, v1, v0, 32 bitop3:0x6c
	v_lshl_add_u32 v130, v2, 12, v4
	v_ashrrev_i32_e32 v2, 31, v0
	v_lshrrev_b32_e32 v2, 26, v2
	v_add_u32_e32 v2, v0, v2
	v_lshlrev_b32_e32 v1, 3, v12
	v_ashrrev_i32_e32 v13, 6, v2
	v_and_b32_e32 v2, 0xc0, v2
	v_and_b32_e32 v1, -16, v1
	v_sub_u32_e32 v0, v0, v2
	v_add_u32_e32 v1, v13, v1
	v_ashrrev_i16_sdwa v0, v3, sext(v0) dst_sel:DWORD dst_unused:UNUSED_PAD src0_sel:DWORD src1_sel:BYTE_0
	v_and_b32_e32 v3, 3, v13
	v_and_or_b32 v3, v1, s1, v3
	s_ashr_i32 s1, s8, 6
	s_ashr_i32 s5, s4, 31
	s_ashr_i32 s85, s84, 31
	s_ashr_i32 s0, s8, 8
	s_lshl_b32 s17, s1, 10
	s_lshl_b64 s[6:7], s[4:5], 20
	s_lshl_b64 s[12:13], s[84:85], 20
	s_add_u32 s88, s80, s12
	v_lshlrev_b32_e32 v4, 5, v12
	v_bfe_i32 v14, v0, 0, 16
	v_lshlrev_b32_e32 v0, 1, v1
	v_lshrrev_b32_e32 v2, 2, v1
	s_addc_u32 s89, s81, s13
	s_add_i32 s28, s17, 0
	v_and_b32_e32 v4, 32, v4
	v_and_b32_e32 v0, 24, v0
	v_and_b32_e32 v2, 4, v2
	s_add_i32 m0, s28, 0x10000
	v_or3_b32 v0, v3, v2, v0
	v_add_lshl_u32 v2, v4, v14, 1
	global_load_lds_dwordx4 v134, s[88:89]
	s_add_i32 m0, s28, 0x12000
	v_lshl_add_u32 v146, v0, 12, v2
	s_add_u32 s12, s88, 0x80000
	global_load_lds_dwordx4 v146, s[88:89]
	s_addc_u32 s13, s89, 0
	s_add_i32 m0, s28, 0x14000
	v_lshl_add_u32 v144, v1, 12, v2
	global_load_lds_dwordx4 v134, s[12:13]
	s_add_i32 m0, s28, 0x16000
	s_add_u32 s86, s48, s6
	s_addc_u32 s87, s49, s7
	s_add_i32 s29, s28, 0x2000
	global_load_lds_dwordx4 v146, s[12:13]
	s_mov_b32 m0, s28
	s_add_u32 s6, s86, 0x80000
	global_load_lds_dwordx4 v130, s[86:87]
	s_mov_b32 m0, s29
	s_addc_u32 s7, s87, 0
	s_add_i32 s71, s28, 0x4000
	global_load_lds_dwordx4 v144, s[86:87]
	s_mov_b32 m0, s71
	s_add_i32 s82, s28, 0x6000
	global_load_lds_dwordx4 v130, s[6:7]
	s_mov_b32 m0, s82
	v_mov_b32_e32 v135, 0
	global_load_lds_dwordx4 v144, s[6:7]
	v_mov_b32_e32 v147, v135
	v_mov_b32_e32 v131, v135
	v_mov_b32_e32 v145, v135
	s_cmp_eq_u32 s0, 1
	s_mov_b64 s[54:55], s[56:57]
	s_mov_b64 s[56:57], s[34:35]
	s_mov_b32 s83, 0
	v_lshl_add_u64 v[6:7], s[88:89], 0, v[134:135]
	v_lshl_add_u64 v[4:5], s[88:89], 0, v[146:147]
	v_lshl_add_u64 v[0:1], s[86:87], 0, v[130:131]
	s_cselect_b64 s[6:7], -1, 0
	s_cmp_lg_u32 s0, 1
	v_lshl_add_u64 v[2:3], s[86:87], 0, v[144:145]
	s_cbranch_scc1 .Lprio_inv_2
	s_barrier
	s_branch .LBB0_264

; #define PG8_STAGE(bufoff, gbase, voff) do { _Pragma("unroll") for (int _i = 0; _i < 2; ++_i) \
;         __builtin_amdgcn_global_load_lds((const unsigned*)((const char*)(gbase) + (voff)[_i]), (LAS unsigned*)(lds + (bufoff) + ldsw + _i * 8192), 16, 0, 0); } while (0)
; #define PG8_BAR __builtin_amdgcn_s_barrier()
;     __host__ __device__ bool next(int i, Unit& u) const {
;         const long L = (long)i * G + c; if (L >= nwg) return false;
;         int wgid = (int)L; { const int q = nwg / NXCD, r = nwg % NXCD, xcd = wgid % NXCD, off = wgid / NXCD; wgid = (xcd < r ? xcd * (q + 1) : r * (q + 1) + (xcd - r) * q) + off; }
;         const int nig = WGM * nN, gid = wgid / nig, fm = gid * WGM, gsz = (nM - fm) < WGM ? (nM - fm) : WGM;
;         u.pm = fm + ((wgid % nig) % gsz); u.pn = (wgid % nig) / gsz; if (cperm) u.pn = (u.pn % 5) * 8 + u.pn / 5; return true;
; template <class Epi, bool ALIGN_EPI, class Hook = NoHook>
; __device__ __forceinline__ void gemm_phase(LAS unsigned char* lds, const Gemm g, const StaticOrder& S, const Epi& E, const Hook& HK = Hook()) {
;     ...
;     for (int i = 0; i < 2; ++i) { int R, C; stage_rc(tid * 16 + i * 8192, R, C); const int Rb = Epi::PERM ? ((R & ~31) + perm32(R & 31)) : R;
;         voffA[i] = (unsigned)(R * g.lda + C) * 2u; voffB[i] = (unsigned)(Rb * g.ldb + C) * 2u; }
;     const size_t kstep = (size_t)(BK * 2);
;     const size_t hstepA = (size_t)HALF * g.lda * 2, hstepB = (size_t)HALF * g.ldb * 2;
;     const size_t tstepA = 2 * hstepA, tstepB = 2 * hstepB;
;     const unsigned ldsw = (unsigned)wid * 1024u;
;     const int aoff = lds_byte(wr * 64 + fr, fq * 8), boff = lds_byte(wc * 32 + fr, fq * 8);
;     ...
;     Unit cur, nxt; int ui = 0;
;     if (!S.next(0, cur)) return;
;     f32x4 acc[2][2][4][2];
; #pragma unroll
;     for (int a = 0; a < 2; ++a)
; #pragma unroll
;         for (int b = 0; b < 2; ++b)
; #pragma unroll
;             for (int m = 0; m < 4; ++m)
; #pragma unroll
;                 for (int n = 0; n < 2; ++n) acc[a][b][m][n] = (f32x4){0.f, 0.f, 0.f, 0.f};
;     bf16x8 At[4][2], B0[2][2], B1[2][2];
;     const char* cA = (const char*)g.A + (size_t)cur.pm * tstepA; const char* cB = (const char*)g.Bt + (size_t)cur.pn * tstepB;
;     PG8_STAGE(PG8_SB(0, 0), cB, voffB); PG8_STAGE(PG8_SB(0, 1), cB + hstepB, voffB); PG8_STAGE(PG8_SA(0, 0), cA, voffA); PG8_STAGE(PG8_SA(0, 1), cA + hstepA, voffA);
;     if (wr == 1) PG8_BAR;
.LBB0_775:
	v_ashrrev_i32_e32 v1, 31, v8
	v_lshrrev_b32_e32 v1, 26, v1
	v_add_u32_e32 v1, v8, v1
	v_ashrrev_i32_e32 v9, 6, v1
	v_bfe_i32 v1, v8, 27, 1
	v_lshlrev_b32_e32 v0, 4, v8
	v_lshrrev_b32_e32 v1, 22, v1
	v_add_u32_e32 v1, v0, v1
	v_and_b32_e32 v1, 0xfffffc00, v1
	v_sub_u32_e32 v1, v0, v1
	v_lshrrev_b32_e32 v2, 4, v1
	v_bitop3_b32 v1, v2, v1, 32 bitop3:0x6c
	v_ashrrev_i32_e32 v3, 31, v1
	v_lshrrev_b32_e32 v3, 26, v3
	v_add_u32_e32 v3, v1, v3
	v_lshlrev_b32_e32 v2, 3, v9
	v_ashrrev_i32_e32 v10, 6, v3
	v_and_b32_e32 v3, 0xc0, v3
	v_and_b32_e32 v2, -16, v2
	v_sub_u32_e32 v1, v1, v3
	v_mov_b32_e32 v3, 1
	v_add_u32_e32 v2, v10, v2
	v_ashrrev_i16_sdwa v1, v3, sext(v1) dst_sel:DWORD dst_unused:UNUSED_PAD src0_sel:DWORD src1_sel:BYTE_0
	s_ashr_i32 s0, s7, 3
	v_lshlrev_b32_e32 v4, 5, v9
	v_bfe_i32 v11, v1, 0, 16
	v_lshlrev_b32_e32 v1, 1, v2
	v_lshrrev_b32_e32 v5, 2, v2
	v_and_b32_e32 v6, 3, v10
	s_mov_b32 s7, 0xfffe0
	v_and_b32_e32 v4, 32, v4
	v_and_b32_e32 v1, 24, v1
	v_and_b32_e32 v5, 4, v5
	v_and_or_b32 v6, v2, s7, v6
	v_or3_b32 v1, v6, v5, v1
	v_add_lshl_u32 v4, v4, v11, 1
	v_add_u32_e32 v0, 0x2000, v0
	v_lshl_add_u32 v130, v1, 12, v4
	v_ashrrev_i32_e32 v1, 31, v0
	v_lshrrev_b32_e32 v1, 22, v1
	v_add_u32_e32 v1, v0, v1
	v_ashrrev_i32_e32 v12, 10, v1
	v_mul_i32_i24_e32 v1, 0x400, v12
	v_sub_u32_e32 v0, v0, v1
	v_lshrrev_b32_e32 v1, 4, v0
	v_bitop3_b32 v0, v1, v0, 32 bitop3:0x6c
	v_lshl_add_u32 v128, v2, 12, v4
	v_ashrrev_i32_e32 v2, 31, v0
	v_lshrrev_b32_e32 v2, 26, v2
	v_add_u32_e32 v2, v0, v2
	s_add_i32 s0, s6, s0
	v_lshlrev_b32_e32 v1, 3, v12
	v_ashrrev_i32_e32 v13, 6, v2
	v_and_b32_e32 v2, 0xc0, v2
	s_ashr_i32 s6, s0, 31
	v_and_b32_e32 v1, -16, v1
	v_sub_u32_e32 v0, v0, v2
	s_lshr_b32 s6, s6, 27
	v_add_u32_e32 v1, v13, v1
	v_ashrrev_i16_sdwa v0, v3, sext(v0) dst_sel:DWORD dst_unused:UNUSED_PAD src0_sel:DWORD src1_sel:BYTE_0
	v_and_b32_e32 v3, 3, v13
	s_add_i32 s6, s0, s6
	v_and_or_b32 v3, v1, s7, v3
	s_ashr_i32 s7, s6, 5
	s_andn2_b32 s6, s6, 31
	s_sub_i32 s6, s0, s6
	s_bfe_i32 s0, s6, 0x80000
	s_bfe_u32 s0, s0, 0x2000d
	s_add_i32 s8, s6, s0
	s_bfe_i32 s0, s8, 0x80000
	s_and_b32 s8, s8, 0xfc
	s_sub_i32 s6, s6, s8
	s_lshl_b32 s7, s7, 2
	s_sext_i32_i16 s0, s0
	s_sext_i32_i8 s6, s6
	s_ashr_i32 s1, s12, 8
	s_lshr_b32 s0, s0, 2
	s_add_i32 s38, s7, s6
	s_ashr_i32 s10, s12, 6
	s_ashr_i32 s39, s38, 31
	s_bfe_i64 s[8:9], s[0:1], 0x100000
	s_lshl_b32 s27, s10, 10
	s_lshl_b64 s[6:7], s[38:39], 20
	s_lshl_b64 s[8:9], s[8:9], 20
	s_add_u32 s42, s74, s8
	v_lshlrev_b32_e32 v4, 5, v12
	v_bfe_i32 v14, v0, 0, 16
	v_lshlrev_b32_e32 v0, 1, v1
	v_lshrrev_b32_e32 v2, 2, v1
	s_addc_u32 s43, s75, s9
	s_add_i32 s28, s27, 0
	v_and_b32_e32 v4, 32, v4
	v_and_b32_e32 v0, 24, v0
	v_and_b32_e32 v2, 4, v2
	s_add_i32 m0, s28, 0x10000
	v_or3_b32 v0, v3, v2, v0
	v_add_lshl_u32 v2, v4, v14, 1
	global_load_lds_dwordx4 v130, s[42:43]
	s_add_i32 m0, s28, 0x12000
	v_lshl_add_u32 v134, v0, 12, v2
	s_add_u32 s8, s42, 0x80000
	global_load_lds_dwordx4 v134, s[42:43]
	s_addc_u32 s9, s43, 0
	s_add_i32 m0, s28, 0x14000
	v_lshl_add_u32 v132, v1, 12, v2
	global_load_lds_dwordx4 v130, s[8:9]
	s_add_i32 m0, s28, 0x16000
	s_add_u32 s40, s66, s6
	s_addc_u32 s41, s67, s7
	s_add_i32 s29, s28, 0x2000
	global_load_lds_dwordx4 v134, s[8:9]
	s_mov_b32 m0, s28
	s_add_u32 s6, s40, 0x80000
	global_load_lds_dwordx4 v128, s[40:41]
	s_mov_b32 m0, s29
	s_addc_u32 s7, s41, 0
	s_add_i32 s39, s28, 0x4000
	global_load_lds_dwordx4 v132, s[40:41]
	s_mov_b32 m0, s39
	s_add_i32 s50, s28, 0x6000
	global_load_lds_dwordx4 v128, s[6:7]
	s_mov_b32 m0, s50
	v_mov_b32_e32 v131, 0
	global_load_lds_dwordx4 v132, s[6:7]
	v_mov_b32_e32 v135, v131
	v_mov_b32_e32 v129, v131
	v_mov_b32_e32 v133, v131
	s_cmp_eq_u32 s1, 1
	s_mov_b32 s51, 0
	v_lshl_add_u64 v[6:7], s[42:43], 0, v[130:131]
	v_lshl_add_u64 v[2:3], s[42:43], 0, v[134:135]
	s_mov_b64 s[6:7], 0x80000
	v_lshl_add_u64 v[0:1], s[40:41], 0, v[128:129]
	s_cselect_b64 s[8:9], -1, 0
	s_cmp_lg_u32 s1, 1
	v_lshl_add_u64 v[4:5], s[40:41], 0, v[132:133]
	s_cbranch_scc1 .Lprio_inv_3
	s_barrier
	s_branch .LBB0_777

; #define PG8_STAGE(bufoff, gbase, voff) do { _Pragma("unroll") for (int _i = 0; _i < 2; ++_i) \
;         __builtin_amdgcn_global_load_lds((const unsigned*)((const char*)(gbase) + (voff)[_i]), (LAS unsigned*)(lds + (bufoff) + ldsw + _i * 8192), 16, 0, 0); } while (0)
; #define PG8_BAR __builtin_amdgcn_s_barrier()
; template <class Epi, bool ALIGN_EPI, class Hook = NoHook>
; __device__ __forceinline__ void gemm_phase(LAS unsigned char* lds, const Gemm g, const StaticOrder& S, const Epi& E, const Hook& HK = Hook()) {
;     ...
;     for (int i = 0; i < 2; ++i) { int R, C; stage_rc(tid * 16 + i * 8192, R, C); const int Rb = Epi::PERM ? ((R & ~31) + perm32(R & 31)) : R;
;         voffA[i] = (unsigned)(R * g.lda + C) * 2u; voffB[i] = (unsigned)(Rb * g.ldb + C) * 2u; }
;     const size_t kstep = (size_t)(BK * 2);
;     const size_t hstepA = (size_t)HALF * g.lda * 2, hstepB = (size_t)HALF * g.ldb * 2;
;     const size_t tstepA = 2 * hstepA, tstepB = 2 * hstepB;
;     const unsigned ldsw = (unsigned)wid * 1024u;
;     const int aoff = lds_byte(wr * 64 + fr, fq * 8), boff = lds_byte(wc * 32 + fr, fq * 8);
;     ...
;     Unit cur, nxt; int ui = 0;
;     if (!S.next(0, cur)) return;
;     f32x4 acc[2][2][4][2];
; #pragma unroll
;     for (int a = 0; a < 2; ++a)
; #pragma unroll
;         for (int b = 0; b < 2; ++b)
; #pragma unroll
;             for (int m = 0; m < 4; ++m)
; #pragma unroll
;                 for (int n = 0; n < 2; ++n) acc[a][b][m][n] = (f32x4){0.f, 0.f, 0.f, 0.f};
;     bf16x8 At[4][2], B0[2][2], B1[2][2];
;     const char* cA = (const char*)g.A + (size_t)cur.pm * tstepA; const char* cB = (const char*)g.Bt + (size_t)cur.pn * tstepB;
;     PG8_STAGE(PG8_SB(0, 0), cB, voffB); PG8_STAGE(PG8_SB(0, 1), cB + hstepB, voffB); PG8_STAGE(PG8_SA(0, 0), cA, voffA); PG8_STAGE(PG8_SA(0, 1), cA + hstepA, voffA);
;     if (wr == 1) PG8_BAR;
.LBB0_910:
	s_or_b64 exec, exec, s[0:1]
	v_readlane_b32 s0, v254, 16
	v_mov_b32_e32 v9, v136
	v_readlane_b32 s1, v254, 17
	s_waitcnt lgkmcnt(0)
	s_barrier
	s_andn2_b64 vcc, exec, s[0:1]
	v_readfirstlane_b32 s1, v9
	s_cbranch_vccnz .LBB0_926
	v_lshlrev_b32_e32 v0, 4, v9
	v_add_u32_e32 v1, 0x2000, v0
	v_ashrrev_i32_e32 v2, 31, v1
	v_lshrrev_b32_e32 v2, 22, v2
	v_add_u32_e32 v2, v1, v2
	v_ashrrev_i32_e32 v8, 10, v2
	v_mul_i32_i24_e32 v2, 0x400, v8
	v_sub_u32_e32 v1, v1, v2
	v_lshrrev_b32_e32 v2, 4, v1
	v_bitop3_b32 v1, v2, v1, 32 bitop3:0x6c
	v_ashrrev_i32_e32 v2, 31, v1
	v_lshrrev_b32_e32 v2, 26, v2
	v_add_u32_e32 v2, v1, v2
	v_lshlrev_b32_e32 v3, 3, v8
	v_ashrrev_i32_e32 v10, 6, v2
	v_and_b32_e32 v3, -16, v3
	v_add_u32_e32 v3, v10, v3
	v_and_b32_e32 v4, 3, v10
	s_mov_b32 s0, 0xfffe0
	v_lshrrev_b32_e32 v5, 2, v3
	v_lshlrev_b32_e32 v6, 1, v3
	v_and_b32_e32 v2, 0xc0, v2
	v_and_or_b32 v4, v3, s0, v4
	v_and_b32_e32 v5, 4, v5
	v_and_b32_e32 v6, 24, v6
	v_sub_u32_e32 v1, v1, v2
	v_mov_b32_e32 v2, 1
	v_or3_b32 v4, v4, v5, v6
	v_lshlrev_b32_e32 v5, 5, v8
	v_ashrrev_i16_sdwa v1, v2, sext(v1) dst_sel:DWORD dst_unused:UNUSED_PAD src0_sel:DWORD src1_sel:BYTE_0
	v_and_b32_e32 v5, 32, v5
	v_bfe_i32 v11, v1, 0, 16
	v_add_lshl_u32 v1, v5, v11, 1
	v_lshl_add_u32 v128, v4, 12, v1
	v_lshl_add_u32 v130, v3, 12, v1
	v_bfe_i32 v1, v9, 27, 1
	v_lshrrev_b32_e32 v1, 22, v1
	v_add_u32_e32 v1, v0, v1
	v_and_b32_e32 v1, 0xfffffc00, v1
	v_sub_u32_e32 v0, v0, v1
	v_lshrrev_b32_e32 v1, 4, v0
	v_ashrrev_i32_e32 v3, 31, v9
	v_bitop3_b32 v0, v1, v0, 32 bitop3:0x6c
	v_lshrrev_b32_e32 v3, 26, v3
	v_ashrrev_i32_e32 v1, 31, v0
	v_add_u32_e32 v3, v9, v3
	v_lshrrev_b32_e32 v1, 26, v1
	v_ashrrev_i32_e32 v13, 6, v3
	v_add_u32_e32 v1, v0, v1
	v_lshlrev_b32_e32 v3, 3, v13
	v_ashrrev_i32_e32 v12, 6, v1
	v_and_b32_e32 v3, -16, v3
	v_add_u32_e32 v3, v12, v3
	v_and_b32_e32 v4, 3, v12
	s_ashr_i32 s26, s2, 31
	v_and_or_b32 v4, v3, s0, v4
	s_lshr_b32 s0, s26, 29
	s_add_i32 s0, s2, s0
	s_ashr_i32 s8, s1, 6
	s_ashr_i32 s6, s0, 3
	s_and_b32 s0, s0, -8
	s_ashr_i32 s10, s1, 8
	s_lshl_b32 s13, s8, 10
	s_sub_i32 s0, s2, s0
	s_cmp_lt_i32 s0, 0
	s_movk_i32 s27, 0x161
	s_cselect_b32 s7, s27, 0x160
	s_mul_i32 s0, s0, s7
	s_add_i32 s0, s0, s6
	s_mul_hi_i32 s6, s0, 0x2e8ba2e9
	s_lshr_b32 s7, s6, 31
	s_ashr_i32 s6, s6, 6
	s_add_i32 s6, s6, s7
	s_lshl_b32 s7, s6, 3
	s_mulk_i32 s6, 0x160
	s_sub_i32 s6, s0, s6
	s_sext_i32_i16 s0, s6
	s_bfe_u32 s0, s0, 0x3001c
	s_add_i32 s9, s6, s0
	s_sext_i32_i16 s0, s9
	s_and_b32 s9, s9, 0xfff8
	s_sub_i32 s6, s6, s9
	s_sext_i32_i16 s6, s6
	v_lshrrev_b32_e32 v5, 2, v3
	v_lshlrev_b32_e32 v6, 1, v3
	v_and_b32_e32 v1, 0xc0, v1
	s_lshr_b32 s0, s0, 3
	s_add_i32 s22, s7, s6
	v_and_b32_e32 v5, 4, v5
	v_and_b32_e32 v6, 24, v6
	v_sub_u32_e32 v0, v0, v1
	s_ashr_i32 s23, s22, 31
	s_bfe_i64 s[14:15], s[0:1], 0x100000
	v_or3_b32 v4, v4, v5, v6
	v_lshlrev_b32_e32 v5, 5, v13
	v_ashrrev_i16_sdwa v0, v2, sext(v0) dst_sel:DWORD dst_unused:UNUSED_PAD src0_sel:DWORD src1_sel:BYTE_0
	s_lshl_b64 s[6:7], s[22:23], 20
	s_lshl_b64 s[14:15], s[14:15], 20
	v_and_b32_e32 v5, 32, v5
	v_bfe_i32 v14, v0, 0, 16
	s_add_u32 s28, s66, s14
	v_add_lshl_u32 v0, v5, v14, 1
	s_addc_u32 s29, s67, s15
	s_add_i32 s23, s13, 0
	v_lshl_add_u32 v132, v4, 12, v0
	s_add_i32 m0, s23, 0x10000
	v_lshl_add_u32 v134, v3, 12, v0
	global_load_lds_dwordx4 v132, s[28:29]
	s_add_i32 m0, s23, 0x12000
	s_add_u32 s14, s28, 0x80000
	global_load_lds_dwordx4 v128, s[28:29]
	s_addc_u32 s15, s29, 0
	s_add_i32 m0, s23, 0x14000
	v_mov_b32_e32 v133, 0
	global_load_lds_dwordx4 v132, s[14:15]
	s_add_i32 m0, s23, 0x16000
	s_add_u32 s24, s48, s6
	s_addc_u32 s25, s49, s7
	s_add_i32 s33, s23, 0x2000
	global_load_lds_dwordx4 v128, s[14:15]
	s_mov_b32 m0, s23
	s_add_u32 s6, s24, 0x80000
	global_load_lds_dwordx4 v134, s[24:25]
	s_mov_b32 m0, s33
	s_addc_u32 s7, s25, 0
	s_add_i32 s38, s23, 0x4000
	global_load_lds_dwordx4 v130, s[24:25]
	s_mov_b32 m0, s38
	s_add_i32 s39, s23, 0x6000
	global_load_lds_dwordx4 v134, s[6:7]
	s_mov_b32 m0, s39
	v_mov_b32_e32 v129, v133
	global_load_lds_dwordx4 v130, s[6:7]
	v_mov_b32_e32 v135, v133
	v_mov_b32_e32 v131, v133
	s_cmp_eq_u32 s10, 1
	s_mov_b32 s40, 0
	v_lshl_add_u64 v[6:7], s[28:29], 0, v[132:133]
	v_lshl_add_u64 v[4:5], s[28:29], 0, v[128:129]
	v_lshl_add_u64 v[0:1], s[24:25], 0, v[134:135]
	s_cselect_b64 s[6:7], -1, 0
	s_cmp_lg_u32 s10, 1
	v_lshl_add_u64 v[2:3], s[24:25], 0, v[130:131]
	s_cbranch_scc1 .Lprio_inv_4
	s_barrier
	s_branch .LBB0_913

; #define PG8_STAGE(bufoff, gbase, voff) do { _Pragma("unroll") for (int _i = 0; _i < 2; ++_i) \
;         __builtin_amdgcn_global_load_lds((const unsigned*)((const char*)(gbase) + (voff)[_i]), (LAS unsigned*)(lds + (bufoff) + ldsw + _i * 8192), 16, 0, 0); } while (0)
; #define PG8_BAR __builtin_amdgcn_s_barrier()
; template <class Epi, bool ALIGN_EPI, class Hook = NoHook>
; __device__ __forceinline__ void gemm_phase(LAS unsigned char* lds, const Gemm g, const StaticOrder& S, const Epi& E, const Hook& HK = Hook()) {
;     ...
;     for (int i = 0; i < 2; ++i) { int R, C; stage_rc(tid * 16 + i * 8192, R, C); const int Rb = Epi::PERM ? ((R & ~31) + perm32(R & 31)) : R;
;         voffA[i] = (unsigned)(R * g.lda + C) * 2u; voffB[i] = (unsigned)(Rb * g.ldb + C) * 2u; }
;     const size_t kstep = (size_t)(BK * 2);
;     const size_t hstepA = (size_t)HALF * g.lda * 2, hstepB = (size_t)HALF * g.ldb * 2;
;     const size_t tstepA = 2 * hstepA, tstepB = 2 * hstepB;
;     const unsigned ldsw = (unsigned)wid * 1024u;
;     const int aoff = lds_byte(wr * 64 + fr, fq * 8), boff = lds_byte(wc * 32 + fr, fq * 8);
;     ...
;     Unit cur, nxt; int ui = 0;
;     if (!S.next(0, cur)) return;
;     f32x4 acc[2][2][4][2];
; #pragma unroll
;     for (int a = 0; a < 2; ++a)
; #pragma unroll
;         for (int b = 0; b < 2; ++b)
; #pragma unroll
;             for (int m = 0; m < 4; ++m)
; #pragma unroll
;                 for (int n = 0; n < 2; ++n) acc[a][b][m][n] = (f32x4){0.f, 0.f, 0.f, 0.f};
;     bf16x8 At[4][2], B0[2][2], B1[2][2];
;     const char* cA = (const char*)g.A + (size_t)cur.pm * tstepA; const char* cB = (const char*)g.Bt + (size_t)cur.pn * tstepB;
;     PG8_STAGE(PG8_SB(0, 0), cB, voffB); PG8_STAGE(PG8_SB(0, 1), cB + hstepB, voffB); PG8_STAGE(PG8_SA(0, 0), cA, voffA); PG8_STAGE(PG8_SA(0, 1), cA + hstepA, voffA);
;     if (wr == 1) PG8_BAR;
.LBB0_983:
	v_ashrrev_i32_e32 v1, 31, v136
	v_lshrrev_b32_e32 v1, 26, v1
	v_add_u32_e32 v1, v136, v1
	v_ashrrev_i32_e32 v8, 6, v1
	v_bfe_i32 v1, v136, 27, 1
	v_lshlrev_b32_e32 v0, 4, v136
	v_lshrrev_b32_e32 v1, 22, v1
	v_add_u32_e32 v1, v0, v1
	v_and_b32_e32 v1, 0xfffffc00, v1
	v_sub_u32_e32 v1, v0, v1
	v_lshrrev_b32_e32 v2, 4, v1
	v_bitop3_b32 v1, v2, v1, 32 bitop3:0x6c
	v_ashrrev_i32_e32 v3, 31, v1
	v_lshrrev_b32_e32 v3, 26, v3
	v_lshlrev_b32_e32 v2, 3, v8
	v_add_u32_e32 v3, v1, v3
	v_and_b32_e32 v2, -16, v2
	v_ashrrev_i32_e32 v9, 6, v3
	v_and_b32_e32 v3, 0xc0, v3
	v_add_u32_e32 v2, v9, v2
	v_lshlrev_b32_e32 v4, 5, v8
	v_sub_u32_e32 v1, v1, v3
	v_mov_b32_e32 v3, 1
	v_and_b32_e32 v10, 32, v4
	v_ashrrev_i16_sdwa v1, v3, sext(v1) dst_sel:DWORD dst_unused:UNUSED_PAD src0_sel:DWORD src1_sel:BYTE_0
	v_lshlrev_b32_e32 v4, 1, v2
	v_lshrrev_b32_e32 v5, 2, v2
	v_and_b32_e32 v6, 3, v9
	s_mov_b32 s7, 0x7fffe0
	v_bfe_i32 v11, v1, 0, 16
	v_and_b32_e32 v4, 24, v4
	v_and_b32_e32 v5, 4, v5
	v_and_or_b32 v6, v2, s7, v6
	s_movk_i32 s1, 0x1600
	v_add_u32_e32 v1, v10, v11
	v_or3_b32 v4, v6, v5, v4
	v_mul_lo_u32 v2, v2, s1
	v_add_lshl_u32 v128, v1, v2, 1
	v_mul_u32_u24_e32 v2, 0x1600, v4
	v_add_u32_e32 v0, 0x2000, v0
	v_add_lshl_u32 v130, v2, v1, 1
	v_ashrrev_i32_e32 v1, 31, v0
	v_lshrrev_b32_e32 v1, 22, v1
	v_add_u32_e32 v1, v0, v1
	v_ashrrev_i32_e32 v12, 10, v1
	v_mul_i32_i24_e32 v1, 0x400, v12
	v_sub_u32_e32 v0, v0, v1
	v_lshrrev_b32_e32 v1, 4, v0
	v_bitop3_b32 v0, v1, v0, 32 bitop3:0x6c
	v_ashrrev_i32_e32 v2, 31, v0
	v_lshrrev_b32_e32 v2, 26, v2
	s_add_i32 s5, s5, s6
	v_lshlrev_b32_e32 v1, 3, v12
	v_add_u32_e32 v2, v0, v2
	s_ashr_i32 s6, s5, 31
	v_and_b32_e32 v1, -16, v1
	v_ashrrev_i32_e32 v13, 6, v2
	v_lshlrev_b32_e32 v4, 5, v12
	s_lshr_b32 s6, s6, 27
	v_add_u32_e32 v1, v13, v1
	v_and_b32_e32 v14, 32, v4
	v_and_b32_e32 v4, 3, v13
	s_add_i32 s6, s5, s6
	v_and_or_b32 v4, v1, s7, v4
	s_ashr_i32 s7, s6, 5
	s_and_b32 s6, s6, 0xffe0
	s_sub_i32 s6, s5, s6
	s_bfe_i32 s5, s6, 0x80000
	s_bfe_u32 s5, s5, 0x2000d
	s_add_i32 s9, s6, s5
	s_bfe_i32 s5, s9, 0x80000
	s_and_b32 s9, s9, 0xfc
	s_sub_i32 s6, s6, s9
	s_lshl_b32 s7, s7, 2
	s_sext_i32_i16 s10, s5
	s_sext_i32_i8 s6, s6
	v_and_b32_e32 v2, 0xc0, v2
	s_ashr_i32 s8, s4, 6
	s_add_i32 s39, s7, s6
	s_ashr_i32 s6, s10, 2
	s_ashr_i32 s0, s4, 8
	v_sub_u32_e32 v0, v0, v2
	s_lshl_b32 s22, s8, 10
	s_lshr_b32 s5, s10, 2
	s_mul_hi_i32 s7, s6, 0x2c0000
	s_mul_i32 s6, s6, 0x2c0000
	v_ashrrev_i16_sdwa v0, v3, sext(v0) dst_sel:DWORD dst_unused:UNUSED_PAD src0_sel:DWORD src1_sel:BYTE_0
	v_lshlrev_b32_e32 v2, 1, v1
	v_lshrrev_b32_e32 v3, 2, v1
	s_add_u32 s16, s88, s6
	v_bfe_i32 v15, v0, 0, 16
	v_and_b32_e32 v2, 24, v2
	v_and_b32_e32 v3, 4, v3
	s_addc_u32 s17, s89, s7
	s_add_i32 s23, s22, 0
	v_add_u32_e32 v0, v14, v15
	v_or3_b32 v2, v4, v3, v2
	v_mul_lo_u32 v1, v1, s1
	s_add_i32 m0, s23, 0x10000
	v_add_lshl_u32 v132, v0, v1, 1
	v_mul_u32_u24_e32 v1, 0x1600, v2
	global_load_lds_dwordx4 v130, s[16:17]
	s_add_i32 m0, s23, 0x12000
	v_add_lshl_u32 v134, v1, v0, 1
	s_add_u32 s6, s16, 0x160000
	global_load_lds_dwordx4 v134, s[16:17]
	s_addc_u32 s7, s17, 0
	s_add_i32 m0, s23, 0x14000
	s_mul_i32 s11, s39, 0x2c0000
	global_load_lds_dwordx4 v130, s[6:7]
	s_add_i32 m0, s23, 0x16000
	s_mul_hi_i32 s9, s39, 0x2c0000
	s_add_u32 s14, s46, s11
	s_addc_u32 s15, s47, s9
	s_add_i32 s24, s23, 0x2000
	global_load_lds_dwordx4 v134, s[6:7]
	s_mov_b32 m0, s23
	s_add_u32 s6, s14, 0x160000
	global_load_lds_dwordx4 v128, s[14:15]
	s_mov_b32 m0, s24
	s_addc_u32 s7, s15, 0
	s_add_i32 s25, s23, 0x4000
	global_load_lds_dwordx4 v132, s[14:15]
	s_mov_b32 m0, s25
	s_add_i32 s26, s23, 0x6000
	global_load_lds_dwordx4 v128, s[6:7]
	s_mov_b32 m0, s26
	v_mov_b32_e32 v131, 0
	global_load_lds_dwordx4 v132, s[6:7]
	v_mov_b32_e32 v135, v131
	v_mov_b32_e32 v129, v131
	v_mov_b32_e32 v133, v131
	s_cmp_eq_u32 s0, 1
	s_mov_b32 s27, 0
	v_lshl_add_u64 v[6:7], s[16:17], 0, v[130:131]
	v_lshl_add_u64 v[2:3], s[16:17], 0, v[134:135]
	s_mov_b32 s12, 0x16000
	v_lshl_add_u64 v[0:1], s[14:15], 0, v[128:129]
	s_cselect_b64 s[6:7], -1, 0
	s_cmp_lg_u32 s0, 1
	v_lshl_add_u64 v[4:5], s[14:15], 0, v[132:133]
	s_cbranch_scc1 .Lprio_inv_5
	s_barrier
	s_branch .LBB0_985
